# up-projection epilogue: store addresses as a 32-bit row*5632+col*2 offset plus a literal per row group with scalar base (no 64-bit multiply-add per group)
# speedup vs baseline: 1.0058x; 1.0058x over previous
.LBB0_382:
	s_waitcnt vmcnt(8)
	v_lshl_or_b32 v144, s29, 7, v156
	v_lshl_add_u32 v164, s28, 8, v1
	v_mul_u32_u24_e32 v146, 0x1600, v164
	s_andn2_b64 vcc, exec, s[6:7]
	v_lshl_add_u32 v146, v144, 1, v146
	v_cvt_f32_u32_e32 v168, v166
	v_fmamk_f32 v170, v168, 0x34800000, v228
	v_rsq_f32_e32 v168, v170
	v_pk_mul_f32 v[122:123], v[126:127], v[122:123]
	v_pk_mul_f32 v[124:125], v[128:129], v[124:125]
	v_pk_mul_f32 v[114:115], v[118:119], v[114:115]
	v_pk_mul_f32 v[116:117], v[120:121], v[116:117]
	v_mul_f32_e32 v172, 0xbfb8aa3b, v168
	v_pk_mul_f32 v[126:127], v[126:127], v[172:173] op_sel_hi:[1,0]
	v_pk_mul_f32 v[128:129], v[128:129], v[172:173] op_sel_hi:[1,0]
	v_pk_mul_f32 v[118:119], v[118:119], v[172:173] op_sel_hi:[1,0]
	v_pk_mul_f32 v[120:121], v[120:121], v[172:173] op_sel_hi:[1,0]
	v_exp_f32_e32 v126, v126
	v_exp_f32_e32 v127, v127
	v_exp_f32_e32 v128, v128
	v_exp_f32_e32 v129, v129
	v_exp_f32_e32 v118, v118
	v_exp_f32_e32 v119, v119
	v_exp_f32_e32 v120, v120
	v_exp_f32_e32 v121, v121
	v_pk_fma_f32 v[126:127], v[126:127], v[170:171], v[170:171] op_sel_hi:[1,0,0]
	v_pk_fma_f32 v[128:129], v[128:129], v[170:171], v[170:171] op_sel_hi:[1,0,0]
	v_pk_fma_f32 v[118:119], v[118:119], v[170:171], v[170:171] op_sel_hi:[1,0,0]
	v_pk_fma_f32 v[120:121], v[120:121], v[170:171], v[170:171] op_sel_hi:[1,0,0]
	v_rcp_f32_e32 v126, v126
	v_rcp_f32_e32 v127, v127
	v_rcp_f32_e32 v128, v128
	v_rcp_f32_e32 v129, v129
	v_rcp_f32_e32 v118, v118
	v_rcp_f32_e32 v119, v119
	v_rcp_f32_e32 v120, v120
	v_rcp_f32_e32 v121, v121
	v_pk_mul_f32 v[122:123], v[122:123], v[126:127]
	v_pk_mul_f32 v[124:125], v[124:125], v[128:129]
	v_pk_mul_f32 v[118:119], v[114:115], v[118:119]
	v_pk_mul_f32 v[120:121], v[116:117], v[120:121]
	v_cvt_pk_bf16_f32 v114, v122, v123
	v_cvt_pk_bf16_f32 v115, v124, v125
	v_cvt_pk_bf16_f32 v116, v118, v119
	v_cvt_pk_bf16_f32 v117, v120, v121
	global_store_dwordx4 v146, v[114:117], s[82:83] sc1
	s_nop 1
	v_cvt_f32_u32_e32 v168, v165
	v_fmamk_f32 v170, v168, 0x34800000, v228
	v_rsq_f32_e32 v168, v170
	v_pk_mul_f32 v[106:107], v[110:111], v[106:107]
	v_pk_mul_f32 v[108:109], v[112:113], v[108:109]
	v_pk_mul_f32 v[98:99], v[102:103], v[98:99]
	v_pk_mul_f32 v[100:101], v[104:105], v[100:101]
	v_mul_f32_e32 v172, 0xbfb8aa3b, v168
	v_pk_mul_f32 v[110:111], v[110:111], v[172:173] op_sel_hi:[1,0]
	v_pk_mul_f32 v[112:113], v[112:113], v[172:173] op_sel_hi:[1,0]
	v_pk_mul_f32 v[102:103], v[102:103], v[172:173] op_sel_hi:[1,0]
	v_pk_mul_f32 v[104:105], v[104:105], v[172:173] op_sel_hi:[1,0]
	v_exp_f32_e32 v110, v110
	v_exp_f32_e32 v111, v111
	v_exp_f32_e32 v112, v112
	v_exp_f32_e32 v113, v113
	v_exp_f32_e32 v102, v102
	v_exp_f32_e32 v103, v103
	v_exp_f32_e32 v104, v104
	v_exp_f32_e32 v105, v105
	v_add_u32_e32 v114, 0x16000, v146
	v_pk_fma_f32 v[110:111], v[110:111], v[170:171], v[170:171] op_sel_hi:[1,0,0]
	v_pk_fma_f32 v[112:113], v[112:113], v[170:171], v[170:171] op_sel_hi:[1,0,0]
	v_pk_fma_f32 v[102:103], v[102:103], v[170:171], v[170:171] op_sel_hi:[1,0,0]
	v_pk_fma_f32 v[104:105], v[104:105], v[170:171], v[170:171] op_sel_hi:[1,0,0]
	v_rcp_f32_e32 v110, v110
	v_rcp_f32_e32 v111, v111
	v_rcp_f32_e32 v112, v112
	v_rcp_f32_e32 v113, v113
	v_rcp_f32_e32 v102, v102
	v_rcp_f32_e32 v103, v103
	v_rcp_f32_e32 v104, v104
	v_rcp_f32_e32 v105, v105
	v_pk_mul_f32 v[106:107], v[106:107], v[110:111]
	v_pk_mul_f32 v[108:109], v[108:109], v[112:113]
	v_pk_mul_f32 v[102:103], v[98:99], v[102:103]
	v_pk_mul_f32 v[104:105], v[100:101], v[104:105]
	v_cvt_pk_bf16_f32 v98, v106, v107
	v_cvt_pk_bf16_f32 v99, v108, v109
	v_cvt_pk_bf16_f32 v100, v102, v103
	v_cvt_pk_bf16_f32 v101, v104, v105
	global_store_dwordx4 v114, v[98:101], s[82:83] sc1
	s_nop 1
	v_cvt_f32_u32_e32 v168, v163
	v_fmamk_f32 v170, v168, 0x34800000, v228
	v_rsq_f32_e32 v168, v170
	v_pk_mul_f32 v[90:91], v[94:95], v[90:91]
	v_pk_mul_f32 v[92:93], v[96:97], v[92:93]
	v_pk_mul_f32 v[82:83], v[86:87], v[82:83]
	v_pk_mul_f32 v[84:85], v[88:89], v[84:85]
	v_mul_f32_e32 v172, 0xbfb8aa3b, v168
	v_pk_mul_f32 v[94:95], v[94:95], v[172:173] op_sel_hi:[1,0]
	v_pk_mul_f32 v[96:97], v[96:97], v[172:173] op_sel_hi:[1,0]
	v_pk_mul_f32 v[86:87], v[86:87], v[172:173] op_sel_hi:[1,0]
	v_pk_mul_f32 v[88:89], v[88:89], v[172:173] op_sel_hi:[1,0]
	v_exp_f32_e32 v94, v94
	v_exp_f32_e32 v95, v95
	v_exp_f32_e32 v96, v96
	v_exp_f32_e32 v97, v97
	v_exp_f32_e32 v86, v86
	v_exp_f32_e32 v87, v87
	v_exp_f32_e32 v88, v88
	v_exp_f32_e32 v89, v89
	v_add_u32_e32 v98, 0x2c000, v146
	v_pk_fma_f32 v[94:95], v[94:95], v[170:171], v[170:171] op_sel_hi:[1,0,0]
	v_pk_fma_f32 v[96:97], v[96:97], v[170:171], v[170:171] op_sel_hi:[1,0,0]
	v_pk_fma_f32 v[86:87], v[86:87], v[170:171], v[170:171] op_sel_hi:[1,0,0]
	v_pk_fma_f32 v[88:89], v[88:89], v[170:171], v[170:171] op_sel_hi:[1,0,0]
	v_rcp_f32_e32 v94, v94
	v_rcp_f32_e32 v95, v95
	v_rcp_f32_e32 v96, v96
	v_rcp_f32_e32 v97, v97
	v_rcp_f32_e32 v86, v86
	v_rcp_f32_e32 v87, v87
	v_rcp_f32_e32 v88, v88
	v_rcp_f32_e32 v89, v89
	v_pk_mul_f32 v[90:91], v[90:91], v[94:95]
	v_pk_mul_f32 v[92:93], v[92:93], v[96:97]
	v_pk_mul_f32 v[86:87], v[82:83], v[86:87]
	v_pk_mul_f32 v[88:89], v[84:85], v[88:89]
	v_cvt_pk_bf16_f32 v82, v90, v91
	v_cvt_pk_bf16_f32 v83, v92, v93
	v_cvt_pk_bf16_f32 v84, v86, v87
	v_cvt_pk_bf16_f32 v85, v88, v89
	global_store_dwordx4 v98, v[82:85], s[82:83] sc1
	s_nop 1
	v_cvt_f32_u32_e32 v168, v162
	v_fmamk_f32 v170, v168, 0x34800000, v228
	v_rsq_f32_e32 v168, v170
	v_pk_mul_f32 v[74:75], v[78:79], v[74:75]
	v_pk_mul_f32 v[76:77], v[80:81], v[76:77]
	v_pk_mul_f32 v[66:67], v[70:71], v[66:67]
	v_pk_mul_f32 v[68:69], v[72:73], v[68:69]
	v_mul_f32_e32 v172, 0xbfb8aa3b, v168
	v_pk_mul_f32 v[78:79], v[78:79], v[172:173] op_sel_hi:[1,0]
	v_pk_mul_f32 v[80:81], v[80:81], v[172:173] op_sel_hi:[1,0]
	v_pk_mul_f32 v[70:71], v[70:71], v[172:173] op_sel_hi:[1,0]
	v_pk_mul_f32 v[72:73], v[72:73], v[172:173] op_sel_hi:[1,0]
	v_exp_f32_e32 v78, v78
	v_exp_f32_e32 v79, v79
	v_exp_f32_e32 v80, v80
	v_exp_f32_e32 v81, v81
	v_exp_f32_e32 v70, v70
	v_exp_f32_e32 v71, v71
	v_exp_f32_e32 v72, v72
	v_exp_f32_e32 v73, v73
	v_add_u32_e32 v82, 0x42000, v146
	v_pk_fma_f32 v[78:79], v[78:79], v[170:171], v[170:171] op_sel_hi:[1,0,0]
	v_pk_fma_f32 v[80:81], v[80:81], v[170:171], v[170:171] op_sel_hi:[1,0,0]
	v_pk_fma_f32 v[70:71], v[70:71], v[170:171], v[170:171] op_sel_hi:[1,0,0]
	v_pk_fma_f32 v[72:73], v[72:73], v[170:171], v[170:171] op_sel_hi:[1,0,0]
	v_rcp_f32_e32 v78, v78
	v_rcp_f32_e32 v79, v79
	v_rcp_f32_e32 v80, v80
	v_rcp_f32_e32 v81, v81
	v_rcp_f32_e32 v70, v70
	v_rcp_f32_e32 v71, v71
	v_rcp_f32_e32 v72, v72
	v_rcp_f32_e32 v73, v73
	v_pk_mul_f32 v[74:75], v[74:75], v[78:79]
	v_pk_mul_f32 v[76:77], v[76:77], v[80:81]
	v_pk_mul_f32 v[70:71], v[66:67], v[70:71]
	v_pk_mul_f32 v[72:73], v[68:69], v[72:73]
	v_cvt_pk_bf16_f32 v66, v74, v75
	v_cvt_pk_bf16_f32 v67, v76, v77
	v_cvt_pk_bf16_f32 v68, v70, v71
	v_cvt_pk_bf16_f32 v69, v72, v73
	global_store_dwordx4 v82, v[66:69], s[82:83] sc1
	s_nop 1
	v_cvt_f32_u32_e32 v168, v161
	v_fmamk_f32 v170, v168, 0x34800000, v228
	v_rsq_f32_e32 v168, v170
	v_pk_mul_f32 v[58:59], v[62:63], v[58:59]
	v_pk_mul_f32 v[60:61], v[64:65], v[60:61]
	v_pk_mul_f32 v[50:51], v[54:55], v[50:51]
	v_pk_mul_f32 v[52:53], v[56:57], v[52:53]
	v_mul_f32_e32 v172, 0xbfb8aa3b, v168
	v_pk_mul_f32 v[62:63], v[62:63], v[172:173] op_sel_hi:[1,0]
	v_pk_mul_f32 v[64:65], v[64:65], v[172:173] op_sel_hi:[1,0]
	v_pk_mul_f32 v[54:55], v[54:55], v[172:173] op_sel_hi:[1,0]
	v_pk_mul_f32 v[56:57], v[56:57], v[172:173] op_sel_hi:[1,0]
	v_exp_f32_e32 v62, v62
	v_exp_f32_e32 v63, v63
	v_exp_f32_e32 v64, v64
	v_exp_f32_e32 v65, v65
	v_exp_f32_e32 v54, v54
	v_exp_f32_e32 v55, v55
	v_exp_f32_e32 v56, v56
	v_exp_f32_e32 v57, v57
	v_add_u32_e32 v66, 0xb0000, v146
	v_pk_fma_f32 v[62:63], v[62:63], v[170:171], v[170:171] op_sel_hi:[1,0,0]
	v_pk_fma_f32 v[64:65], v[64:65], v[170:171], v[170:171] op_sel_hi:[1,0,0]
	v_pk_fma_f32 v[54:55], v[54:55], v[170:171], v[170:171] op_sel_hi:[1,0,0]
	v_pk_fma_f32 v[56:57], v[56:57], v[170:171], v[170:171] op_sel_hi:[1,0,0]
	v_rcp_f32_e32 v62, v62
	v_rcp_f32_e32 v63, v63
	v_rcp_f32_e32 v64, v64
	v_rcp_f32_e32 v65, v65
	v_rcp_f32_e32 v54, v54
	v_rcp_f32_e32 v55, v55
	v_rcp_f32_e32 v56, v56
	v_rcp_f32_e32 v57, v57
	v_pk_mul_f32 v[58:59], v[58:59], v[62:63]
	v_pk_mul_f32 v[60:61], v[60:61], v[64:65]
	v_pk_mul_f32 v[54:55], v[50:51], v[54:55]
	v_pk_mul_f32 v[56:57], v[52:53], v[56:57]
	v_cvt_pk_bf16_f32 v50, v58, v59
	v_cvt_pk_bf16_f32 v51, v60, v61
	v_cvt_pk_bf16_f32 v52, v54, v55
	v_cvt_pk_bf16_f32 v53, v56, v57
	global_store_dwordx4 v66, v[50:53], s[82:83] sc1
	s_nop 1
	v_cvt_f32_u32_e32 v168, v160
	v_fmamk_f32 v170, v168, 0x34800000, v228
	v_rsq_f32_e32 v168, v170
	v_pk_mul_f32 v[42:43], v[46:47], v[42:43]
	v_pk_mul_f32 v[44:45], v[48:49], v[44:45]
	v_pk_mul_f32 v[34:35], v[38:39], v[34:35]
	v_pk_mul_f32 v[36:37], v[40:41], v[36:37]
	v_mul_f32_e32 v172, 0xbfb8aa3b, v168
	v_pk_mul_f32 v[46:47], v[46:47], v[172:173] op_sel_hi:[1,0]
	v_pk_mul_f32 v[48:49], v[48:49], v[172:173] op_sel_hi:[1,0]
	v_pk_mul_f32 v[38:39], v[38:39], v[172:173] op_sel_hi:[1,0]
	v_pk_mul_f32 v[40:41], v[40:41], v[172:173] op_sel_hi:[1,0]
	v_exp_f32_e32 v46, v46
	v_exp_f32_e32 v47, v47
	v_exp_f32_e32 v48, v48
	v_exp_f32_e32 v49, v49
	v_exp_f32_e32 v38, v38
	v_exp_f32_e32 v39, v39
	v_exp_f32_e32 v40, v40
	v_exp_f32_e32 v41, v41
	v_add_u32_e32 v50, 0xc6000, v146
	v_pk_fma_f32 v[46:47], v[46:47], v[170:171], v[170:171] op_sel_hi:[1,0,0]
	v_pk_fma_f32 v[48:49], v[48:49], v[170:171], v[170:171] op_sel_hi:[1,0,0]
	v_pk_fma_f32 v[38:39], v[38:39], v[170:171], v[170:171] op_sel_hi:[1,0,0]
	v_pk_fma_f32 v[40:41], v[40:41], v[170:171], v[170:171] op_sel_hi:[1,0,0]
	v_rcp_f32_e32 v46, v46
	v_rcp_f32_e32 v47, v47
	v_rcp_f32_e32 v48, v48
	v_rcp_f32_e32 v49, v49
	v_rcp_f32_e32 v38, v38
	v_rcp_f32_e32 v39, v39
	v_rcp_f32_e32 v40, v40
	v_rcp_f32_e32 v41, v41
	v_pk_mul_f32 v[42:43], v[42:43], v[46:47]
	v_pk_mul_f32 v[44:45], v[44:45], v[48:49]
	v_pk_mul_f32 v[38:39], v[34:35], v[38:39]
	v_pk_mul_f32 v[40:41], v[36:37], v[40:41]
	v_cvt_pk_bf16_f32 v34, v42, v43
	v_cvt_pk_bf16_f32 v35, v44, v45
	v_cvt_pk_bf16_f32 v36, v38, v39
	v_cvt_pk_bf16_f32 v37, v40, v41
	global_store_dwordx4 v50, v[34:37], s[82:83] sc1
	s_nop 1
	v_cvt_f32_u32_e32 v168, v159
	v_fmamk_f32 v170, v168, 0x34800000, v228
	v_rsq_f32_e32 v168, v170
	v_pk_mul_f32 v[26:27], v[30:31], v[26:27]
	v_pk_mul_f32 v[28:29], v[32:33], v[28:29]
	v_pk_mul_f32 v[18:19], v[22:23], v[18:19]
	v_pk_mul_f32 v[20:21], v[24:25], v[20:21]
	v_mul_f32_e32 v172, 0xbfb8aa3b, v168
	v_pk_mul_f32 v[30:31], v[30:31], v[172:173] op_sel_hi:[1,0]
	v_pk_mul_f32 v[32:33], v[32:33], v[172:173] op_sel_hi:[1,0]
	v_pk_mul_f32 v[22:23], v[22:23], v[172:173] op_sel_hi:[1,0]
	v_pk_mul_f32 v[24:25], v[24:25], v[172:173] op_sel_hi:[1,0]
	v_exp_f32_e32 v30, v30
	v_exp_f32_e32 v31, v31
	v_exp_f32_e32 v32, v32
	v_exp_f32_e32 v33, v33
	v_exp_f32_e32 v22, v22
	v_exp_f32_e32 v23, v23
	v_exp_f32_e32 v24, v24
	v_exp_f32_e32 v25, v25
	v_add_u32_e32 v34, 0xdc000, v146
	v_pk_fma_f32 v[30:31], v[30:31], v[170:171], v[170:171] op_sel_hi:[1,0,0]
	v_pk_fma_f32 v[32:33], v[32:33], v[170:171], v[170:171] op_sel_hi:[1,0,0]
	v_pk_fma_f32 v[22:23], v[22:23], v[170:171], v[170:171] op_sel_hi:[1,0,0]
	v_pk_fma_f32 v[24:25], v[24:25], v[170:171], v[170:171] op_sel_hi:[1,0,0]
	v_rcp_f32_e32 v30, v30
	v_rcp_f32_e32 v31, v31
	v_rcp_f32_e32 v32, v32
	v_rcp_f32_e32 v33, v33
	v_rcp_f32_e32 v22, v22
	v_rcp_f32_e32 v23, v23
	v_rcp_f32_e32 v24, v24
	v_rcp_f32_e32 v25, v25
	v_pk_mul_f32 v[26:27], v[26:27], v[30:31]
	v_pk_mul_f32 v[28:29], v[28:29], v[32:33]
	v_pk_mul_f32 v[22:23], v[18:19], v[22:23]
	v_pk_mul_f32 v[24:25], v[20:21], v[24:25]
	v_cvt_pk_bf16_f32 v18, v26, v27
	v_cvt_pk_bf16_f32 v19, v28, v29
	v_cvt_pk_bf16_f32 v20, v22, v23
	v_cvt_pk_bf16_f32 v21, v24, v25
	global_store_dwordx4 v34, v[18:21], s[82:83] sc1
	s_nop 1
	v_cvt_f32_u32_e32 v168, v158
	v_fmamk_f32 v170, v168, 0x34800000, v228
	v_rsq_f32_e32 v168, v170
	v_pk_mul_f32 v[10:11], v[14:15], v[10:11]
	v_pk_mul_f32 v[12:13], v[16:17], v[12:13]
	v_pk_mul_f32 v[2:3], v[6:7], v[2:3]
	v_pk_mul_f32 v[4:5], v[8:9], v[4:5]
	v_mul_f32_e32 v172, 0xbfb8aa3b, v168
	v_pk_mul_f32 v[14:15], v[14:15], v[172:173] op_sel_hi:[1,0]
	v_pk_mul_f32 v[16:17], v[16:17], v[172:173] op_sel_hi:[1,0]
	v_pk_mul_f32 v[6:7], v[6:7], v[172:173] op_sel_hi:[1,0]
	v_pk_mul_f32 v[8:9], v[8:9], v[172:173] op_sel_hi:[1,0]
	v_exp_f32_e32 v14, v14
	v_exp_f32_e32 v15, v15
	v_exp_f32_e32 v16, v16
	v_exp_f32_e32 v17, v17
	v_exp_f32_e32 v6, v6
	v_exp_f32_e32 v7, v7
	v_exp_f32_e32 v8, v8
	v_exp_f32_e32 v9, v9
	v_add_u32_e32 v18, 0xf2000, v146
	v_pk_fma_f32 v[14:15], v[14:15], v[170:171], v[170:171] op_sel_hi:[1,0,0]
	v_pk_fma_f32 v[16:17], v[16:17], v[170:171], v[170:171] op_sel_hi:[1,0,0]
	v_pk_fma_f32 v[6:7], v[6:7], v[170:171], v[170:171] op_sel_hi:[1,0,0]
	v_pk_fma_f32 v[8:9], v[8:9], v[170:171], v[170:171] op_sel_hi:[1,0,0]
	v_rcp_f32_e32 v14, v14
	v_rcp_f32_e32 v15, v15
	v_rcp_f32_e32 v16, v16
	v_rcp_f32_e32 v17, v17
	v_rcp_f32_e32 v6, v6
	v_rcp_f32_e32 v7, v7
	v_rcp_f32_e32 v8, v8
	v_rcp_f32_e32 v9, v9
	v_pk_mul_f32 v[10:11], v[10:11], v[14:15]
	v_pk_mul_f32 v[12:13], v[12:13], v[16:17]
	v_pk_mul_f32 v[6:7], v[2:3], v[6:7]
	v_pk_mul_f32 v[8:9], v[4:5], v[8:9]
	v_cvt_pk_bf16_f32 v2, v10, v11
	v_cvt_pk_bf16_f32 v3, v12, v13
	v_cvt_pk_bf16_f32 v4, v6, v7
	v_cvt_pk_bf16_f32 v5, v8, v9
	global_store_dwordx4 v18, v[2:5], s[82:83] sc1
	s_nop 1
	s_mov_b64 s[28:29], -1
	s_cbranch_vccnz .LBB0_359
	s_cmpk_eq_i32 s98, 0x100
	s_cbranch_scc1 .Lsw_rsu_keep
	s_lshl_b32 s6, s22, 8
	v_add_u32_e32 v2, s6, v1
	v_ashrrev_i32_e32 v3, 31, v2
	v_lshl_add_u64 v[2:3], v[2:3], 2, s[12:13]
	global_load_dword v166, v[2:3], off
	v_add_u32_e32 v2, s6, v148
	v_ashrrev_i32_e32 v3, 31, v2
	v_lshl_add_u64 v[2:3], v[2:3], 2, s[12:13]
	global_load_dword v165, v[2:3], off
	v_add_u32_e32 v2, s6, v149
	v_ashrrev_i32_e32 v3, 31, v2
	v_lshl_add_u64 v[2:3], v[2:3], 2, s[12:13]
	global_load_dword v163, v[2:3], off
	v_add_u32_e32 v2, s6, v150
	v_ashrrev_i32_e32 v3, 31, v2
	v_lshl_add_u64 v[2:3], v[2:3], 2, s[12:13]
	global_load_dword v162, v[2:3], off
	v_add_u32_e32 v2, s6, v151
	v_ashrrev_i32_e32 v3, 31, v2
	v_lshl_add_u64 v[2:3], v[2:3], 2, s[12:13]
	global_load_dword v161, v[2:3], off
	v_add_u32_e32 v2, s6, v152
	v_ashrrev_i32_e32 v3, 31, v2
	v_lshl_add_u64 v[2:3], v[2:3], 2, s[12:13]
	global_load_dword v160, v[2:3], off
	v_add_u32_e32 v2, s6, v153
	v_ashrrev_i32_e32 v3, 31, v2
	v_lshl_add_u64 v[2:3], v[2:3], 2, s[12:13]
	global_load_dword v159, v[2:3], off
	v_add_u32_e32 v2, s6, v154
	v_ashrrev_i32_e32 v3, 31, v2
	v_lshl_add_u64 v[2:3], v[2:3], 2, s[12:13]
	global_load_dword v158, v[2:3], off
